# v21 = v7 + all safe work reductions: K-loop LDS address hoist, merged waits, attention address hoist, barrier census loads together, 64-bit accumulator zeroing
# baseline (speedup 1.0000x reference)
.LBB0_37:
	s_add_u32 s21, s10, 0x100
	v_mov_b64_e32 v[0:1], 0
	s_addc_u32 s90, s11, 0
	s_mov_b32 s22, -2
	v_mov_b64_e32 v[2:3], 0
	v_mov_b64_e32 v[4:5], 0
	v_mov_b64_e32 v[6:7], 0
	v_mov_b64_e32 v[16:17], 0
	v_mov_b64_e32 v[18:19], 0
	v_mov_b64_e32 v[20:21], 0
	v_mov_b64_e32 v[22:23], 0
	v_mov_b64_e32 v[32:33], 0
	v_mov_b64_e32 v[34:35], 0
	v_mov_b64_e32 v[36:37], 0
	v_mov_b64_e32 v[38:39], 0
	v_mov_b64_e32 v[48:49], 0
	v_mov_b64_e32 v[50:51], 0
	v_mov_b64_e32 v[52:53], 0
	v_mov_b64_e32 v[54:55], 0
	v_mov_b64_e32 v[8:9], 0
	v_mov_b64_e32 v[10:11], 0
	v_mov_b64_e32 v[12:13], 0
	v_mov_b64_e32 v[14:15], 0
	v_mov_b64_e32 v[24:25], 0
	v_mov_b64_e32 v[26:27], 0
	v_mov_b64_e32 v[28:29], 0
	v_mov_b64_e32 v[30:31], 0
	v_mov_b64_e32 v[40:41], 0
	v_mov_b64_e32 v[42:43], 0
	v_mov_b64_e32 v[44:45], 0
	v_mov_b64_e32 v[46:47], 0
	v_mov_b64_e32 v[56:57], 0
	v_mov_b64_e32 v[58:59], 0
	v_mov_b64_e32 v[60:61], 0
	v_mov_b64_e32 v[62:63], 0
	v_mov_b64_e32 v[64:65], 0
	v_mov_b64_e32 v[66:67], 0
	v_mov_b64_e32 v[68:69], 0
	v_mov_b64_e32 v[70:71], 0
	v_mov_b64_e32 v[80:81], 0
	v_mov_b64_e32 v[82:83], 0
	v_mov_b64_e32 v[84:85], 0
	v_mov_b64_e32 v[86:87], 0
	v_mov_b64_e32 v[96:97], 0
	v_mov_b64_e32 v[98:99], 0
	v_mov_b64_e32 v[100:101], 0
	v_mov_b64_e32 v[102:103], 0
	v_mov_b64_e32 v[112:113], 0
	v_mov_b64_e32 v[114:115], 0
	v_mov_b64_e32 v[116:117], 0
	v_mov_b64_e32 v[118:119], 0
	v_mov_b64_e32 v[72:73], 0
	v_mov_b64_e32 v[74:75], 0
	v_mov_b64_e32 v[76:77], 0
	v_mov_b64_e32 v[78:79], 0
	v_mov_b64_e32 v[88:89], 0
	v_mov_b64_e32 v[90:91], 0
	v_mov_b64_e32 v[92:93], 0
	v_mov_b64_e32 v[94:95], 0
	v_mov_b64_e32 v[104:105], 0
	v_mov_b64_e32 v[106:107], 0
	v_mov_b64_e32 v[108:109], 0
	v_mov_b64_e32 v[110:111], 0
	v_mov_b64_e32 v[120:121], 0
	v_mov_b64_e32 v[122:123], 0
	v_mov_b64_e32 v[124:125], 0
	v_mov_b64_e32 v[126:127], 0
	v_add_u32_e32 v159, 0x10000, v143

.LBB0_55:
	s_ashr_i32 s37, s36, 31
	s_lshl_b64 s[14:15], s[36:37], 19
	s_add_u32 s44, s24, s14
	s_addc_u32 s45, s25, s15
	s_and_b64 s[14:15], s[38:39], exec
	s_cselect_b32 s20, s45, s13
	s_cselect_b32 s37, s44, s12
	s_ashr_i32 s41, s40, 31
	s_lshl_b64 s[14:15], s[40:41], 19
	s_add_u32 s92, s26, s14
	s_addc_u32 s93, s27, s15
	s_and_b64 s[14:15], s[38:39], exec
	s_cselect_b32 s41, s93, s11
	s_cselect_b32 s91, s92, s10
	s_add_u32 s96, s10, 0x100
	s_addc_u32 s21, s11, 0
	s_add_u32 s10, s12, 0x40080
	v_mov_b64_e32 v[4:5], 0
	s_addc_u32 s11, s13, 0
	s_mov_b32 s22, -2
	v_mov_b64_e32 v[6:7], 0
	v_mov_b64_e32 v[8:9], 0
	v_mov_b64_e32 v[10:11], 0
	v_mov_b64_e32 v[20:21], 0
	v_mov_b64_e32 v[22:23], 0
	v_mov_b64_e32 v[24:25], 0
	v_mov_b64_e32 v[26:27], 0
	v_mov_b64_e32 v[36:37], 0
	v_mov_b64_e32 v[38:39], 0
	v_mov_b64_e32 v[40:41], 0
	v_mov_b64_e32 v[42:43], 0
	v_mov_b64_e32 v[52:53], 0
	v_mov_b64_e32 v[54:55], 0
	v_mov_b64_e32 v[56:57], 0
	v_mov_b64_e32 v[58:59], 0
	v_mov_b64_e32 v[0:1], 0
	v_mov_b64_e32 v[2:3], 0
	v_mov_b64_e32 v[12:13], 0
	v_mov_b64_e32 v[14:15], 0
	v_mov_b64_e32 v[16:17], 0
	v_mov_b64_e32 v[18:19], 0
	v_mov_b64_e32 v[28:29], 0
	v_mov_b64_e32 v[30:31], 0
	v_mov_b64_e32 v[32:33], 0
	v_mov_b64_e32 v[34:35], 0
	v_mov_b64_e32 v[44:45], 0
	v_mov_b64_e32 v[46:47], 0
	v_mov_b64_e32 v[48:49], 0
	v_mov_b64_e32 v[50:51], 0
	v_mov_b64_e32 v[60:61], 0
	v_mov_b64_e32 v[62:63], 0
	v_mov_b64_e32 v[68:69], 0
	v_mov_b64_e32 v[70:71], 0
	v_mov_b64_e32 v[72:73], 0
	v_mov_b64_e32 v[74:75], 0
	v_mov_b64_e32 v[80:81], 0
	v_mov_b64_e32 v[82:83], 0
	v_mov_b64_e32 v[88:89], 0
	v_mov_b64_e32 v[90:91], 0
	v_mov_b64_e32 v[96:97], 0
	v_mov_b64_e32 v[98:99], 0
	v_mov_b64_e32 v[104:105], 0
	v_mov_b64_e32 v[106:107], 0
	v_mov_b64_e32 v[112:113], 0
	v_mov_b64_e32 v[114:115], 0
	v_mov_b64_e32 v[120:121], 0
	v_mov_b64_e32 v[122:123], 0
	v_mov_b64_e32 v[64:65], 0
	v_mov_b64_e32 v[66:67], 0
	v_mov_b64_e32 v[76:77], 0
	v_mov_b64_e32 v[78:79], 0
	v_mov_b64_e32 v[84:85], 0
	v_mov_b64_e32 v[86:87], 0
	v_mov_b64_e32 v[92:93], 0
	v_mov_b64_e32 v[94:95], 0
	v_mov_b64_e32 v[100:101], 0
	v_mov_b64_e32 v[102:103], 0
	v_mov_b64_e32 v[108:109], 0
	v_mov_b64_e32 v[110:111], 0
	v_mov_b64_e32 v[116:117], 0
	v_mov_b64_e32 v[118:119], 0
	v_mov_b64_e32 v[124:125], 0
	v_mov_b64_e32 v[126:127], 0
	v_add_u32_e32 v159, 0x10000, v147

.LBB0_83:
	s_ashr_i32 s37, s36, 31
	s_lshl_b64 s[20:21], s[36:37], 19
	s_add_u32 s92, s24, s20
	s_addc_u32 s93, s25, s21
	s_and_b64 s[20:21], s[40:41], exec
	s_cselect_b32 s9, s93, s15
	s_cselect_b32 s20, s92, s14
	s_ashr_i32 s45, s44, 31
	s_lshl_b64 s[48:49], s[44:45], 19
	s_add_u32 s96, s26, s48
	s_addc_u32 s97, s27, s49
	s_and_b64 s[48:49], s[40:41], exec
	s_cselect_b32 s37, s97, s13
	s_cselect_b32 s45, s96, s12
	s_add_u32 s90, s12, 0x100
	s_addc_u32 s21, s13, 0
	s_add_u32 vcc_lo, s14, 0x40080
	v_mov_b64_e32 v[0:1], 0
	s_addc_u32 vcc_hi, s15, 0
	s_mov_b32 s22, -2
	v_mov_b64_e32 v[2:3], 0
	v_mov_b64_e32 v[4:5], 0
	v_mov_b64_e32 v[6:7], 0
	v_mov_b64_e32 v[16:17], 0
	v_mov_b64_e32 v[18:19], 0
	v_mov_b64_e32 v[20:21], 0
	v_mov_b64_e32 v[22:23], 0
	v_mov_b64_e32 v[32:33], 0
	v_mov_b64_e32 v[34:35], 0
	v_mov_b64_e32 v[36:37], 0
	v_mov_b64_e32 v[38:39], 0
	v_mov_b64_e32 v[48:49], 0
	v_mov_b64_e32 v[50:51], 0
	v_mov_b64_e32 v[52:53], 0
	v_mov_b64_e32 v[54:55], 0
	v_mov_b64_e32 v[8:9], 0
	v_mov_b64_e32 v[10:11], 0
	v_mov_b64_e32 v[12:13], 0
	v_mov_b64_e32 v[14:15], 0
	v_mov_b64_e32 v[24:25], 0
	v_mov_b64_e32 v[26:27], 0
	v_mov_b64_e32 v[28:29], 0
	v_mov_b64_e32 v[30:31], 0
	v_mov_b64_e32 v[40:41], 0
	v_mov_b64_e32 v[42:43], 0
	v_mov_b64_e32 v[44:45], 0
	v_mov_b64_e32 v[46:47], 0
	v_mov_b64_e32 v[56:57], 0
	v_mov_b64_e32 v[58:59], 0
	v_mov_b64_e32 v[60:61], 0
	v_mov_b64_e32 v[62:63], 0
	v_mov_b64_e32 v[64:65], 0
	v_mov_b64_e32 v[66:67], 0
	v_mov_b64_e32 v[68:69], 0
	v_mov_b64_e32 v[70:71], 0
	v_mov_b64_e32 v[80:81], 0
	v_mov_b64_e32 v[82:83], 0
	v_mov_b64_e32 v[84:85], 0
	v_mov_b64_e32 v[86:87], 0
	v_mov_b64_e32 v[96:97], 0
	v_mov_b64_e32 v[98:99], 0
	v_mov_b64_e32 v[100:101], 0
	v_mov_b64_e32 v[102:103], 0
	v_mov_b64_e32 v[112:113], 0
	v_mov_b64_e32 v[114:115], 0
	v_mov_b64_e32 v[116:117], 0
	v_mov_b64_e32 v[118:119], 0
	v_mov_b64_e32 v[72:73], 0
	v_mov_b64_e32 v[74:75], 0
	v_mov_b64_e32 v[76:77], 0
	v_mov_b64_e32 v[78:79], 0
	v_mov_b64_e32 v[88:89], 0
	v_mov_b64_e32 v[90:91], 0
	v_mov_b64_e32 v[92:93], 0
	v_mov_b64_e32 v[94:95], 0
	v_mov_b64_e32 v[104:105], 0
	v_mov_b64_e32 v[106:107], 0
	v_mov_b64_e32 v[108:109], 0
	v_mov_b64_e32 v[110:111], 0
	v_mov_b64_e32 v[120:121], 0
	v_mov_b64_e32 v[122:123], 0
	v_mov_b64_e32 v[124:125], 0
	v_mov_b64_e32 v[126:127], 0
	v_add_u32_e32 v159, 0x10000, v143

.LBB0_138:
	s_ashr_i32 s41, s40, 31
	s_lshl_b64 s[12:13], s[40:41], 19
	s_add_u32 s12, s25, s12
	s_addc_u32 s13, s26, s13
	s_and_b64 s[14:15], s[38:39], exec
	s_cselect_b32 s9, s13, s93
	s_cselect_b32 s41, s12, s92
	s_ashr_i32 s45, s44, 31
	s_lshl_b64 s[14:15], s[44:45], 19
	s_add_u32 s96, s27, s14
	s_addc_u32 s97, s28, s15
	s_and_b64 s[14:15], s[38:39], exec
	s_cselect_b32 s45, s97, s11
	s_cselect_b32 vcc_lo, s96, s10
	s_add_u32 vcc_hi, s10, 0x100
	s_addc_u32 s21, s11, 0
	s_add_u32 s10, s92, 0x40080
	v_mov_b64_e32 v[0:1], 0
	s_addc_u32 s11, s93, 0
	s_mov_b32 s22, -2
	v_mov_b64_e32 v[2:3], 0
	v_mov_b64_e32 v[4:5], 0
	v_mov_b64_e32 v[6:7], 0
	v_mov_b64_e32 v[16:17], 0
	v_mov_b64_e32 v[18:19], 0
	v_mov_b64_e32 v[20:21], 0
	v_mov_b64_e32 v[22:23], 0
	v_mov_b64_e32 v[32:33], 0
	v_mov_b64_e32 v[34:35], 0
	v_mov_b64_e32 v[36:37], 0
	v_mov_b64_e32 v[38:39], 0
	v_mov_b64_e32 v[48:49], 0
	v_mov_b64_e32 v[50:51], 0
	v_mov_b64_e32 v[52:53], 0
	v_mov_b64_e32 v[54:55], 0
	v_mov_b64_e32 v[8:9], 0
	v_mov_b64_e32 v[10:11], 0
	v_mov_b64_e32 v[12:13], 0
	v_mov_b64_e32 v[14:15], 0
	v_mov_b64_e32 v[24:25], 0
	v_mov_b64_e32 v[26:27], 0
	v_mov_b64_e32 v[28:29], 0
	v_mov_b64_e32 v[30:31], 0
	v_mov_b64_e32 v[40:41], 0
	v_mov_b64_e32 v[42:43], 0
	v_mov_b64_e32 v[44:45], 0
	v_mov_b64_e32 v[46:47], 0
	v_mov_b64_e32 v[56:57], 0
	v_mov_b64_e32 v[58:59], 0
	v_mov_b64_e32 v[60:61], 0
	v_mov_b64_e32 v[62:63], 0
	v_mov_b64_e32 v[64:65], 0
	v_mov_b64_e32 v[66:67], 0
	v_mov_b64_e32 v[68:69], 0
	v_mov_b64_e32 v[70:71], 0
	v_mov_b64_e32 v[80:81], 0
	v_mov_b64_e32 v[82:83], 0
	v_mov_b64_e32 v[84:85], 0
	v_mov_b64_e32 v[86:87], 0
	v_mov_b64_e32 v[96:97], 0
	v_mov_b64_e32 v[98:99], 0
	v_mov_b64_e32 v[100:101], 0
	v_mov_b64_e32 v[102:103], 0
	v_mov_b64_e32 v[112:113], 0
	v_mov_b64_e32 v[114:115], 0
	v_mov_b64_e32 v[116:117], 0
	v_mov_b64_e32 v[118:119], 0
	v_mov_b64_e32 v[72:73], 0
	v_mov_b64_e32 v[74:75], 0
	v_mov_b64_e32 v[76:77], 0
	v_mov_b64_e32 v[78:79], 0
	v_mov_b64_e32 v[88:89], 0
	v_mov_b64_e32 v[90:91], 0
	v_mov_b64_e32 v[92:93], 0
	v_mov_b64_e32 v[94:95], 0
	v_mov_b64_e32 v[104:105], 0
	v_mov_b64_e32 v[106:107], 0
	v_mov_b64_e32 v[108:109], 0
	v_mov_b64_e32 v[110:111], 0
	v_mov_b64_e32 v[120:121], 0
	v_mov_b64_e32 v[122:123], 0
	v_mov_b64_e32 v[124:125], 0
	v_mov_b64_e32 v[126:127], 0
	v_add_u32_e32 v162, 0x10000, v202

.LBB0_177:
	s_add_u32 s21, s10, 0x100
	v_mov_b64_e32 v[0:1], 0
	s_addc_u32 s96, s11, 0
	s_mov_b32 s22, -2
	v_mov_b64_e32 v[2:3], 0
	v_mov_b64_e32 v[4:5], 0
	v_mov_b64_e32 v[6:7], 0
	v_mov_b64_e32 v[16:17], 0
	v_mov_b64_e32 v[18:19], 0
	v_mov_b64_e32 v[20:21], 0
	v_mov_b64_e32 v[22:23], 0
	v_mov_b64_e32 v[32:33], 0
	v_mov_b64_e32 v[34:35], 0
	v_mov_b64_e32 v[36:37], 0
	v_mov_b64_e32 v[38:39], 0
	v_mov_b64_e32 v[48:49], 0
	v_mov_b64_e32 v[50:51], 0
	v_mov_b64_e32 v[52:53], 0
	v_mov_b64_e32 v[54:55], 0
	v_mov_b64_e32 v[8:9], 0
	v_mov_b64_e32 v[10:11], 0
	v_mov_b64_e32 v[12:13], 0
	v_mov_b64_e32 v[14:15], 0
	v_mov_b64_e32 v[24:25], 0
	v_mov_b64_e32 v[26:27], 0
	v_mov_b64_e32 v[28:29], 0
	v_mov_b64_e32 v[30:31], 0
	v_mov_b64_e32 v[40:41], 0
	v_mov_b64_e32 v[42:43], 0
	v_mov_b64_e32 v[44:45], 0
	v_mov_b64_e32 v[46:47], 0
	v_mov_b64_e32 v[56:57], 0
	v_mov_b64_e32 v[58:59], 0
	v_mov_b64_e32 v[60:61], 0
	v_mov_b64_e32 v[62:63], 0
	v_mov_b64_e32 v[64:65], 0
	v_mov_b64_e32 v[66:67], 0
	v_mov_b64_e32 v[68:69], 0
	v_mov_b64_e32 v[70:71], 0
	v_mov_b64_e32 v[80:81], 0
	v_mov_b64_e32 v[82:83], 0
	v_mov_b64_e32 v[84:85], 0
	v_mov_b64_e32 v[86:87], 0
	v_mov_b64_e32 v[96:97], 0
	v_mov_b64_e32 v[98:99], 0
	v_mov_b64_e32 v[100:101], 0
	v_mov_b64_e32 v[102:103], 0
	v_mov_b64_e32 v[112:113], 0
	v_mov_b64_e32 v[114:115], 0
	v_mov_b64_e32 v[116:117], 0
	v_mov_b64_e32 v[118:119], 0
	v_mov_b64_e32 v[72:73], 0
	v_mov_b64_e32 v[74:75], 0
	v_mov_b64_e32 v[76:77], 0
	v_mov_b64_e32 v[78:79], 0
	v_mov_b64_e32 v[88:89], 0
	v_mov_b64_e32 v[90:91], 0
	v_mov_b64_e32 v[92:93], 0
	v_mov_b64_e32 v[94:95], 0
	v_mov_b64_e32 v[104:105], 0
	v_mov_b64_e32 v[106:107], 0
	v_mov_b64_e32 v[108:109], 0
	v_mov_b64_e32 v[110:111], 0
	v_mov_b64_e32 v[120:121], 0
	v_mov_b64_e32 v[122:123], 0
	v_mov_b64_e32 v[124:125], 0
	v_mov_b64_e32 v[126:127], 0
	v_add_u32_e32 v159, 0x10000, v143

.LBB0_211:
	s_ashr_i32 s37, s36, 31
	s_lshl_b64 s[14:15], s[36:37], 19
	s_add_u32 s44, s24, s14
	s_addc_u32 s45, s25, s15
	s_and_b64 s[14:15], s[38:39], exec
	s_cselect_b32 s20, s45, s13
	s_cselect_b32 s37, s44, s12
	s_ashr_i32 s41, s40, 31
	s_lshl_b64 s[14:15], s[40:41], 19
	s_add_u32 s92, s26, s14
	s_addc_u32 s93, s27, s15
	s_and_b64 s[14:15], s[38:39], exec
	s_cselect_b32 s41, s93, s11
	s_cselect_b32 s91, s92, s10
	s_add_u32 s96, s10, 0x100
	s_addc_u32 s97, s11, 0
	s_add_u32 s10, s12, 0x40080
	v_mov_b64_e32 v[4:5], 0
	s_addc_u32 s11, s13, 0
	s_mov_b32 s21, -2
	v_mov_b64_e32 v[6:7], 0
	v_mov_b64_e32 v[8:9], 0
	v_mov_b64_e32 v[10:11], 0
	v_mov_b64_e32 v[20:21], 0
	v_mov_b64_e32 v[22:23], 0
	v_mov_b64_e32 v[24:25], 0
	v_mov_b64_e32 v[26:27], 0
	v_mov_b64_e32 v[36:37], 0
	v_mov_b64_e32 v[38:39], 0
	v_mov_b64_e32 v[40:41], 0
	v_mov_b64_e32 v[42:43], 0
	v_mov_b64_e32 v[52:53], 0
	v_mov_b64_e32 v[54:55], 0
	v_mov_b64_e32 v[56:57], 0
	v_mov_b64_e32 v[58:59], 0
	v_mov_b64_e32 v[0:1], 0
	v_mov_b64_e32 v[2:3], 0
	v_mov_b64_e32 v[12:13], 0
	v_mov_b64_e32 v[14:15], 0
	v_mov_b64_e32 v[16:17], 0
	v_mov_b64_e32 v[18:19], 0
	v_mov_b64_e32 v[28:29], 0
	v_mov_b64_e32 v[30:31], 0
	v_mov_b64_e32 v[32:33], 0
	v_mov_b64_e32 v[34:35], 0
	v_mov_b64_e32 v[44:45], 0
	v_mov_b64_e32 v[46:47], 0
	v_mov_b64_e32 v[48:49], 0
	v_mov_b64_e32 v[50:51], 0
	v_mov_b64_e32 v[60:61], 0
	v_mov_b64_e32 v[62:63], 0
	v_mov_b64_e32 v[68:69], 0
	v_mov_b64_e32 v[70:71], 0
	v_mov_b64_e32 v[72:73], 0
	v_mov_b64_e32 v[74:75], 0
	v_mov_b64_e32 v[80:81], 0
	v_mov_b64_e32 v[82:83], 0
	v_mov_b64_e32 v[88:89], 0
	v_mov_b64_e32 v[90:91], 0
	v_mov_b64_e32 v[96:97], 0
	v_mov_b64_e32 v[98:99], 0
	v_mov_b64_e32 v[104:105], 0
	v_mov_b64_e32 v[106:107], 0
	v_mov_b64_e32 v[112:113], 0
	v_mov_b64_e32 v[114:115], 0
	v_mov_b64_e32 v[120:121], 0
	v_mov_b64_e32 v[122:123], 0
	v_mov_b64_e32 v[64:65], 0
	v_mov_b64_e32 v[66:67], 0
	v_mov_b64_e32 v[76:77], 0
	v_mov_b64_e32 v[78:79], 0
	v_mov_b64_e32 v[84:85], 0
	v_mov_b64_e32 v[86:87], 0
	v_mov_b64_e32 v[92:93], 0
	v_mov_b64_e32 v[94:95], 0
	v_mov_b64_e32 v[100:101], 0
	v_mov_b64_e32 v[102:103], 0
	v_mov_b64_e32 v[108:109], 0
	v_mov_b64_e32 v[110:111], 0
	v_mov_b64_e32 v[116:117], 0
	v_mov_b64_e32 v[118:119], 0
	v_mov_b64_e32 v[124:125], 0
	v_mov_b64_e32 v[126:127], 0
	v_add_u32_e32 v159, 0x10000, v147

.LBB0_309:
	s_ashr_i32 s9, s8, 31
	s_lshl_b64 s[14:15], s[8:9], 19
	s_add_u32 s14, s24, s14
	s_addc_u32 s15, s25, s15
	s_and_b64 s[20:21], s[40:41], exec
	s_cselect_b32 s9, s15, s93
	s_cselect_b32 s20, s14, s92
	s_ashr_i32 s11, s10, 31
	s_lshl_b64 s[90:91], s[10:11], 19
	s_add_u32 s96, s26, s90
	s_addc_u32 s97, s27, s91
	s_and_b64 s[90:91], s[40:41], exec
	s_cselect_b32 s11, s97, s13
	s_cselect_b32 s45, s96, s12
	s_add_u32 s90, s12, 0x100
	s_addc_u32 s91, s13, 0
	s_add_u32 vcc_lo, s92, 0x40080
	v_mov_b64_e32 v[0:1], 0
	s_addc_u32 vcc_hi, s93, 0
	s_mov_b32 s21, -2
	v_mov_b64_e32 v[2:3], 0
	v_mov_b64_e32 v[4:5], 0
	v_mov_b64_e32 v[6:7], 0
	v_mov_b64_e32 v[16:17], 0
	v_mov_b64_e32 v[18:19], 0
	v_mov_b64_e32 v[20:21], 0
	v_mov_b64_e32 v[22:23], 0
	v_mov_b64_e32 v[32:33], 0
	v_mov_b64_e32 v[34:35], 0
	v_mov_b64_e32 v[36:37], 0
	v_mov_b64_e32 v[38:39], 0
	v_mov_b64_e32 v[48:49], 0
	v_mov_b64_e32 v[50:51], 0
	v_mov_b64_e32 v[52:53], 0
	v_mov_b64_e32 v[54:55], 0
	v_mov_b64_e32 v[8:9], 0
	v_mov_b64_e32 v[10:11], 0
	v_mov_b64_e32 v[12:13], 0
	v_mov_b64_e32 v[14:15], 0
	v_mov_b64_e32 v[24:25], 0
	v_mov_b64_e32 v[26:27], 0
	v_mov_b64_e32 v[28:29], 0
	v_mov_b64_e32 v[30:31], 0
	v_mov_b64_e32 v[40:41], 0
	v_mov_b64_e32 v[42:43], 0
	v_mov_b64_e32 v[44:45], 0
	v_mov_b64_e32 v[46:47], 0
	v_mov_b64_e32 v[56:57], 0
	v_mov_b64_e32 v[58:59], 0
	v_mov_b64_e32 v[60:61], 0
	v_mov_b64_e32 v[62:63], 0
	v_mov_b64_e32 v[64:65], 0
	v_mov_b64_e32 v[66:67], 0
	v_mov_b64_e32 v[68:69], 0
	v_mov_b64_e32 v[70:71], 0
	v_mov_b64_e32 v[80:81], 0
	v_mov_b64_e32 v[82:83], 0
	v_mov_b64_e32 v[84:85], 0
	v_mov_b64_e32 v[86:87], 0
	v_mov_b64_e32 v[96:97], 0
	v_mov_b64_e32 v[98:99], 0
	v_mov_b64_e32 v[100:101], 0
	v_mov_b64_e32 v[102:103], 0
	v_mov_b64_e32 v[112:113], 0
	v_mov_b64_e32 v[114:115], 0
	v_mov_b64_e32 v[116:117], 0
	v_mov_b64_e32 v[118:119], 0
	v_mov_b64_e32 v[72:73], 0
	v_mov_b64_e32 v[74:75], 0
	v_mov_b64_e32 v[76:77], 0
	v_mov_b64_e32 v[78:79], 0
	v_mov_b64_e32 v[88:89], 0
	v_mov_b64_e32 v[90:91], 0
	v_mov_b64_e32 v[92:93], 0
	v_mov_b64_e32 v[94:95], 0
	v_mov_b64_e32 v[104:105], 0
	v_mov_b64_e32 v[106:107], 0
	v_mov_b64_e32 v[108:109], 0
	v_mov_b64_e32 v[110:111], 0
	v_mov_b64_e32 v[120:121], 0
	v_mov_b64_e32 v[122:123], 0
	v_mov_b64_e32 v[124:125], 0
	v_mov_b64_e32 v[126:127], 0
	v_add_u32_e32 v159, 0x10000, v143

.LBB0_398:
	s_ashr_i32 s7, s6, 31
	s_lshl_b64 s[2:3], s[6:7], 19
	s_add_u32 s2, s13, s2
	s_addc_u32 s3, s14, s3
	s_and_b64 s[4:5], s[38:39], exec
	s_cselect_b32 s7, s3, s9
	s_cselect_b32 s19, s2, s8
	s_ashr_i32 s97, s96, 31
	s_lshl_b64 s[4:5], s[96:97], 19
	s_add_u32 s4, s15, s4
	s_addc_u32 s5, s24, s5
	s_and_b64 s[10:11], s[38:39], exec
	s_cselect_b32 s20, s5, s1
	s_cselect_b32 s33, s4, s0
	s_add_u32 s90, s0, 0x100
	s_addc_u32 s91, s1, 0
	s_add_u32 s0, s8, 0x40080
	v_mov_b64_e32 v[0:1], 0
	s_addc_u32 s1, s9, 0
	s_mov_b32 s21, -2
	v_mov_b64_e32 v[2:3], 0
	v_mov_b64_e32 v[8:9], 0
	v_mov_b64_e32 v[10:11], 0
	v_mov_b64_e32 v[16:17], 0
	v_mov_b64_e32 v[18:19], 0
	v_mov_b64_e32 v[24:25], 0
	v_mov_b64_e32 v[26:27], 0
	v_mov_b64_e32 v[32:33], 0
	v_mov_b64_e32 v[34:35], 0
	v_mov_b64_e32 v[40:41], 0
	v_mov_b64_e32 v[42:43], 0
	v_mov_b64_e32 v[48:49], 0
	v_mov_b64_e32 v[50:51], 0
	v_mov_b64_e32 v[56:57], 0
	v_mov_b64_e32 v[58:59], 0
	v_mov_b64_e32 v[4:5], 0
	v_mov_b64_e32 v[6:7], 0
	v_mov_b64_e32 v[12:13], 0
	v_mov_b64_e32 v[14:15], 0
	v_mov_b64_e32 v[20:21], 0
	v_mov_b64_e32 v[22:23], 0
	v_mov_b64_e32 v[28:29], 0
	v_mov_b64_e32 v[30:31], 0
	v_mov_b64_e32 v[36:37], 0
	v_mov_b64_e32 v[38:39], 0
	v_mov_b64_e32 v[44:45], 0
	v_mov_b64_e32 v[46:47], 0
	v_mov_b64_e32 v[52:53], 0
	v_mov_b64_e32 v[54:55], 0
	v_mov_b64_e32 v[60:61], 0
	v_mov_b64_e32 v[62:63], 0
	v_mov_b64_e32 v[64:65], 0
	v_mov_b64_e32 v[66:67], 0
	v_mov_b64_e32 v[72:73], 0
	v_mov_b64_e32 v[74:75], 0
	v_mov_b64_e32 v[80:81], 0
	v_mov_b64_e32 v[82:83], 0
	v_mov_b64_e32 v[88:89], 0
	v_mov_b64_e32 v[90:91], 0
	v_mov_b64_e32 v[96:97], 0
	v_mov_b64_e32 v[98:99], 0
	v_mov_b64_e32 v[104:105], 0
	v_mov_b64_e32 v[106:107], 0
	v_mov_b64_e32 v[112:113], 0
	v_mov_b64_e32 v[114:115], 0
	v_mov_b64_e32 v[120:121], 0
	v_mov_b64_e32 v[122:123], 0
	v_mov_b64_e32 v[68:69], 0
	v_mov_b64_e32 v[70:71], 0
	v_mov_b64_e32 v[76:77], 0
	v_mov_b64_e32 v[78:79], 0
	v_mov_b64_e32 v[84:85], 0
	v_mov_b64_e32 v[86:87], 0
	v_mov_b64_e32 v[92:93], 0
	v_mov_b64_e32 v[94:95], 0
	v_mov_b64_e32 v[100:101], 0
	v_mov_b64_e32 v[102:103], 0
	v_mov_b64_e32 v[108:109], 0
	v_mov_b64_e32 v[110:111], 0
	v_mov_b64_e32 v[116:117], 0
	v_mov_b64_e32 v[118:119], 0
	v_mov_b64_e32 v[124:125], 0
	v_mov_b64_e32 v[126:127], 0
	v_add_u32_e32 v163, 0x10000, v157

.LBB0_438:
	s_add_u32 s21, s10, 0x100
	v_mov_b64_e32 v[0:1], 0
	s_addc_u32 s92, s11, 0
	s_mov_b32 s22, -2
	v_mov_b64_e32 v[2:3], 0
	v_mov_b64_e32 v[4:5], 0
	v_mov_b64_e32 v[6:7], 0
	v_mov_b64_e32 v[16:17], 0
	v_mov_b64_e32 v[18:19], 0
	v_mov_b64_e32 v[20:21], 0
	v_mov_b64_e32 v[22:23], 0
	v_mov_b64_e32 v[32:33], 0
	v_mov_b64_e32 v[34:35], 0
	v_mov_b64_e32 v[36:37], 0
	v_mov_b64_e32 v[38:39], 0
	v_mov_b64_e32 v[48:49], 0
	v_mov_b64_e32 v[50:51], 0
	v_mov_b64_e32 v[52:53], 0
	v_mov_b64_e32 v[54:55], 0
	v_mov_b64_e32 v[8:9], 0
	v_mov_b64_e32 v[10:11], 0
	v_mov_b64_e32 v[12:13], 0
	v_mov_b64_e32 v[14:15], 0
	v_mov_b64_e32 v[24:25], 0
	v_mov_b64_e32 v[26:27], 0
	v_mov_b64_e32 v[28:29], 0
	v_mov_b64_e32 v[30:31], 0
	v_mov_b64_e32 v[40:41], 0
	v_mov_b64_e32 v[42:43], 0
	v_mov_b64_e32 v[44:45], 0
	v_mov_b64_e32 v[46:47], 0
	v_mov_b64_e32 v[56:57], 0
	v_mov_b64_e32 v[58:59], 0
	v_mov_b64_e32 v[60:61], 0
	v_mov_b64_e32 v[62:63], 0
	v_mov_b64_e32 v[64:65], 0
	v_mov_b64_e32 v[66:67], 0
	v_mov_b64_e32 v[68:69], 0
	v_mov_b64_e32 v[70:71], 0
	v_mov_b64_e32 v[80:81], 0
	v_mov_b64_e32 v[82:83], 0
	v_mov_b64_e32 v[84:85], 0
	v_mov_b64_e32 v[86:87], 0
	v_mov_b64_e32 v[96:97], 0
	v_mov_b64_e32 v[98:99], 0
	v_mov_b64_e32 v[100:101], 0
	v_mov_b64_e32 v[102:103], 0
	v_mov_b64_e32 v[112:113], 0
	v_mov_b64_e32 v[114:115], 0
	v_mov_b64_e32 v[116:117], 0
	v_mov_b64_e32 v[118:119], 0
	v_mov_b64_e32 v[72:73], 0
	v_mov_b64_e32 v[74:75], 0
	v_mov_b64_e32 v[76:77], 0
	v_mov_b64_e32 v[78:79], 0
	v_mov_b64_e32 v[88:89], 0
	v_mov_b64_e32 v[90:91], 0
	v_mov_b64_e32 v[92:93], 0
	v_mov_b64_e32 v[94:95], 0
	v_mov_b64_e32 v[104:105], 0
	v_mov_b64_e32 v[106:107], 0
	v_mov_b64_e32 v[108:109], 0
	v_mov_b64_e32 v[110:111], 0
	v_mov_b64_e32 v[120:121], 0
	v_mov_b64_e32 v[122:123], 0
	v_mov_b64_e32 v[124:125], 0
	v_mov_b64_e32 v[126:127], 0
	v_add_u32_e32 v159, 0x10000, v143

.LBB0_473:
	s_ashr_i32 s37, s36, 31
	s_lshl_b64 s[14:15], s[36:37], 19
	s_add_u32 s44, s24, s14
	s_addc_u32 s45, s25, s15
	s_and_b64 s[14:15], s[38:39], exec
	s_cselect_b32 s20, s45, s13
	s_cselect_b32 s37, s44, s12
	s_ashr_i32 s41, s40, 31
	s_lshl_b64 s[14:15], s[40:41], 19
	s_add_u32 s46, s26, s14
	s_addc_u32 s47, s27, s15
	s_and_b64 s[14:15], s[38:39], exec
	s_cselect_b32 s41, s47, s11
	s_cselect_b32 s91, s46, s10
	s_add_u32 s92, s10, 0x100
	s_addc_u32 s93, s11, 0
	s_add_u32 s10, s12, 0x40080
	v_mov_b64_e32 v[4:5], 0
	s_addc_u32 s11, s13, 0
	s_mov_b32 s21, -2
	v_mov_b64_e32 v[6:7], 0
	v_mov_b64_e32 v[8:9], 0
	v_mov_b64_e32 v[10:11], 0
	v_mov_b64_e32 v[20:21], 0
	v_mov_b64_e32 v[22:23], 0
	v_mov_b64_e32 v[24:25], 0
	v_mov_b64_e32 v[26:27], 0
	v_mov_b64_e32 v[36:37], 0
	v_mov_b64_e32 v[38:39], 0
	v_mov_b64_e32 v[40:41], 0
	v_mov_b64_e32 v[42:43], 0
	v_mov_b64_e32 v[52:53], 0
	v_mov_b64_e32 v[54:55], 0
	v_mov_b64_e32 v[56:57], 0
	v_mov_b64_e32 v[58:59], 0
	v_mov_b64_e32 v[0:1], 0
	v_mov_b64_e32 v[2:3], 0
	v_mov_b64_e32 v[12:13], 0
	v_mov_b64_e32 v[14:15], 0
	v_mov_b64_e32 v[16:17], 0
	v_mov_b64_e32 v[18:19], 0
	v_mov_b64_e32 v[28:29], 0
	v_mov_b64_e32 v[30:31], 0
	v_mov_b64_e32 v[32:33], 0
	v_mov_b64_e32 v[34:35], 0
	v_mov_b64_e32 v[44:45], 0
	v_mov_b64_e32 v[46:47], 0
	v_mov_b64_e32 v[48:49], 0
	v_mov_b64_e32 v[50:51], 0
	v_mov_b64_e32 v[60:61], 0
	v_mov_b64_e32 v[62:63], 0
	v_mov_b64_e32 v[68:69], 0
	v_mov_b64_e32 v[70:71], 0
	v_mov_b64_e32 v[72:73], 0
	v_mov_b64_e32 v[74:75], 0
	v_mov_b64_e32 v[80:81], 0
	v_mov_b64_e32 v[82:83], 0
	v_mov_b64_e32 v[88:89], 0
	v_mov_b64_e32 v[90:91], 0
	v_mov_b64_e32 v[96:97], 0
	v_mov_b64_e32 v[98:99], 0
	v_mov_b64_e32 v[104:105], 0
	v_mov_b64_e32 v[106:107], 0
	v_mov_b64_e32 v[112:113], 0
	v_mov_b64_e32 v[114:115], 0
	v_mov_b64_e32 v[120:121], 0
	v_mov_b64_e32 v[122:123], 0
	v_mov_b64_e32 v[64:65], 0
	v_mov_b64_e32 v[66:67], 0
	v_mov_b64_e32 v[76:77], 0
	v_mov_b64_e32 v[78:79], 0
	v_mov_b64_e32 v[84:85], 0
	v_mov_b64_e32 v[86:87], 0
	v_mov_b64_e32 v[92:93], 0
	v_mov_b64_e32 v[94:95], 0
	v_mov_b64_e32 v[100:101], 0
	v_mov_b64_e32 v[102:103], 0
	v_mov_b64_e32 v[108:109], 0
	v_mov_b64_e32 v[110:111], 0
	v_mov_b64_e32 v[116:117], 0
	v_mov_b64_e32 v[118:119], 0
	v_mov_b64_e32 v[124:125], 0
	v_mov_b64_e32 v[126:127], 0
	v_add_u32_e32 v159, 0x10000, v147
